# union: lists-phase prefix with 32 loads in flight per chunk + LN-folded epilogue load hoists (6 epilogues) + barrier L1 invalidate at arrival, on top of the EpiResid<1> overlap
# baseline (speedup 1.0000x reference)
; __device__ __forceinline__ void lists_phase(const Args& a, int tid, int lane, int wave) {
;     ...
;     for (int wv = BID * NWAVES + wave; wv < Bn * 8 * (S / 64); wv += nwv) {
;         const int bh = __builtin_amdgcn_readfirstlane(wv / (S / 64)), w = __builtin_amdgcn_readfirstlane(wv % (S / 64));
;         const int t = w * 64 + lane, blk = w >> 2;
;         unsigned off = 0u;
;         { const unsigned* wc_ = WCNT + (size_t)bh * 128 * 32 + (lane & 31); unsigned o0 = 0u, o1 = 0u, o2 = 0u, o3 = 0u; int w2 = 0;
;           for (; w2 + 4 <= w; w2 += 4) { o0 += wc_[(w2 + 0) * 32]; o1 += wc_[(w2 + 1) * 32]; o2 += wc_[(w2 + 2) * 32]; o3 += wc_[(w2 + 3) * 32]; }
;           for (; w2 < w; ++w2) o0 += wc_[w2 * 32];
;           off = (o0 + o1) + (o2 + o3); }
.LBB0_636:
	s_ashr_i32 s6, s3, 31
	s_lshr_b32 s6, s6, 25
	s_add_i32 s6, s3, s6
	s_ashr_i32 s10, s6, 7
	s_and_b32 s6, s6, 0xffffff80
	s_ashr_i32 s11, s10, 31
	s_sub_i32 s19, s3, s6
	s_sub_i32 s98, 0x7f, s19
	s_cmpk_lt_i32 s3, 0x800
	s_cselect_b32 s19, s19, s98
	s_lshl_b64 s[12:13], s[10:11], 14
	s_add_u32 s12, s14, s12
	s_addc_u32 s13, s15, s13
	v_lshl_add_u64 v[8:9], s[12:13], 0, v[6:7]
	v_mov_b32_e32 v10, 0
	v_mov_b32_e32 v11, 0
	v_mov_b32_e32 v12, 0
	v_mov_b32_e32 v13, 0
	s_mov_b32 s20, 0
	s_cmp_lt_i32 s19, 1
	s_cbranch_scc1 .LBB0_652
.Lpf_chunk:
	s_sub_i32 s21, s19, s20
	s_lshl_b32 s6, s20, 7
	v_lshl_add_u64 v[14:15], s[6:7], 0, v[8:9]
	v_mov_b32_e32 v32, 0
	v_mov_b32_e32 v33, 0
	v_mov_b32_e32 v34, 0
	v_mov_b32_e32 v35, 0
	v_mov_b32_e32 v36, 0
	v_mov_b32_e32 v37, 0
	v_mov_b32_e32 v38, 0
	v_mov_b32_e32 v39, 0
	v_mov_b32_e32 v40, 0
	v_mov_b32_e32 v41, 0
	v_mov_b32_e32 v42, 0
	v_mov_b32_e32 v43, 0
	v_mov_b32_e32 v44, 0
	v_mov_b32_e32 v45, 0
	v_mov_b32_e32 v46, 0
	v_mov_b32_e32 v47, 0
	v_mov_b32_e32 v48, 0
	v_mov_b32_e32 v49, 0
	v_mov_b32_e32 v50, 0
	v_mov_b32_e32 v51, 0
	v_mov_b32_e32 v52, 0
	v_mov_b32_e32 v53, 0
	v_mov_b32_e32 v54, 0
	v_mov_b32_e32 v55, 0
	v_mov_b32_e32 v56, 0
	v_mov_b32_e32 v57, 0
	v_mov_b32_e32 v58, 0
	v_mov_b32_e32 v59, 0
	v_mov_b32_e32 v60, 0
	v_mov_b32_e32 v61, 0
	v_mov_b32_e32 v62, 0
	v_mov_b32_e32 v63, 0
	global_load_dword v32, v[14:15], off
	s_cmp_lt_i32 s21, 2
	s_cbranch_scc1 .Lpf_wait
	global_load_dword v33, v[14:15], off offset:128
	s_cmp_lt_i32 s21, 3
	s_cbranch_scc1 .Lpf_wait
	global_load_dword v34, v[14:15], off offset:256
	s_cmp_lt_i32 s21, 4
	s_cbranch_scc1 .Lpf_wait
	global_load_dword v35, v[14:15], off offset:384
	s_cmp_lt_i32 s21, 5
	s_cbranch_scc1 .Lpf_wait
	global_load_dword v36, v[14:15], off offset:512
	s_cmp_lt_i32 s21, 6
	s_cbranch_scc1 .Lpf_wait
	global_load_dword v37, v[14:15], off offset:640
	s_cmp_lt_i32 s21, 7
	s_cbranch_scc1 .Lpf_wait
	global_load_dword v38, v[14:15], off offset:768
	s_cmp_lt_i32 s21, 8
	s_cbranch_scc1 .Lpf_wait
	global_load_dword v39, v[14:15], off offset:896
	s_cmp_lt_i32 s21, 9
	s_cbranch_scc1 .Lpf_wait
	global_load_dword v40, v[14:15], off offset:1024
	s_cmp_lt_i32 s21, 10
	s_cbranch_scc1 .Lpf_wait
	global_load_dword v41, v[14:15], off offset:1152
	s_cmp_lt_i32 s21, 11
	s_cbranch_scc1 .Lpf_wait
	global_load_dword v42, v[14:15], off offset:1280
	s_cmp_lt_i32 s21, 12
	s_cbranch_scc1 .Lpf_wait
	global_load_dword v43, v[14:15], off offset:1408
	s_cmp_lt_i32 s21, 13
	s_cbranch_scc1 .Lpf_wait
	global_load_dword v44, v[14:15], off offset:1536
	s_cmp_lt_i32 s21, 14
	s_cbranch_scc1 .Lpf_wait
	global_load_dword v45, v[14:15], off offset:1664
	s_cmp_lt_i32 s21, 15
	s_cbranch_scc1 .Lpf_wait
	global_load_dword v46, v[14:15], off offset:1792
	s_cmp_lt_i32 s21, 16
	s_cbranch_scc1 .Lpf_wait
	global_load_dword v47, v[14:15], off offset:1920
	s_cmp_lt_i32 s21, 17
	s_cbranch_scc1 .Lpf_wait
	global_load_dword v48, v[14:15], off offset:2048
	s_cmp_lt_i32 s21, 18
	s_cbranch_scc1 .Lpf_wait
	global_load_dword v49, v[14:15], off offset:2176
	s_cmp_lt_i32 s21, 19
	s_cbranch_scc1 .Lpf_wait
	global_load_dword v50, v[14:15], off offset:2304
	s_cmp_lt_i32 s21, 20
	s_cbranch_scc1 .Lpf_wait
	global_load_dword v51, v[14:15], off offset:2432
	s_cmp_lt_i32 s21, 21
	s_cbranch_scc1 .Lpf_wait
	global_load_dword v52, v[14:15], off offset:2560
	s_cmp_lt_i32 s21, 22
	s_cbranch_scc1 .Lpf_wait
	global_load_dword v53, v[14:15], off offset:2688
	s_cmp_lt_i32 s21, 23
	s_cbranch_scc1 .Lpf_wait
	global_load_dword v54, v[14:15], off offset:2816
	s_cmp_lt_i32 s21, 24
	s_cbranch_scc1 .Lpf_wait
	global_load_dword v55, v[14:15], off offset:2944
	s_cmp_lt_i32 s21, 25
	s_cbranch_scc1 .Lpf_wait
	global_load_dword v56, v[14:15], off offset:3072
	s_cmp_lt_i32 s21, 26
	s_cbranch_scc1 .Lpf_wait
	global_load_dword v57, v[14:15], off offset:3200
	s_cmp_lt_i32 s21, 27
	s_cbranch_scc1 .Lpf_wait
	global_load_dword v58, v[14:15], off offset:3328
	s_cmp_lt_i32 s21, 28
	s_cbranch_scc1 .Lpf_wait
	global_load_dword v59, v[14:15], off offset:3456
	s_cmp_lt_i32 s21, 29
	s_cbranch_scc1 .Lpf_wait
	global_load_dword v60, v[14:15], off offset:3584
	s_cmp_lt_i32 s21, 30
	s_cbranch_scc1 .Lpf_wait
	global_load_dword v61, v[14:15], off offset:3712
	s_cmp_lt_i32 s21, 31
	s_cbranch_scc1 .Lpf_wait
	global_load_dword v62, v[14:15], off offset:3840
	s_cmp_lt_i32 s21, 32
	s_cbranch_scc1 .Lpf_wait
	global_load_dword v63, v[14:15], off offset:3968
.Lpf_wait:
	s_add_i32 s20, s20, 32
	s_waitcnt vmcnt(0)
	v_add3_u32 v10, v10, v32, v33
	v_add3_u32 v11, v11, v34, v35
	v_add3_u32 v12, v12, v36, v37
	v_add3_u32 v13, v13, v38, v39
	v_add3_u32 v10, v10, v40, v41
	v_add3_u32 v11, v11, v42, v43
	v_add3_u32 v12, v12, v44, v45
	v_add3_u32 v13, v13, v46, v47
	v_add3_u32 v10, v10, v48, v49
	v_add3_u32 v11, v11, v50, v51
	v_add3_u32 v12, v12, v52, v53
	v_add3_u32 v13, v13, v54, v55
	v_add3_u32 v10, v10, v56, v57
	v_add3_u32 v11, v11, v58, v59
	v_add3_u32 v12, v12, v60, v61
	v_add3_u32 v13, v13, v62, v63
	s_cmp_lt_i32 s20, s19
	s_cbranch_scc1 .Lpf_chunk
